# v11 minus the 8 now-redundant s_waitcnt lgkmcnt(0) after the permlane row-max exchanges in attention
# speedup vs baseline: 1.0028x; 1.0028x over previous
; DI void attn_block(const bf16_t* Q, const bf16_t* Kb, const bf16_t* Vt, bf16_t* AO, LAS unsigned char* lds, int bh, int qb, int tid, int wave, int lane) {
;     ...
;             float mx = -1e30f;
; #pragma unroll
;             for (int kb = 0; kb < 2; ++kb)
; #pragma unroll
;                 for (int i = 0; i < 16; ++i) mx = fmaxf(mx, sa[kb][i]);
;             mx = fmaxf(mx, __shfl_xor(mx, 32));
;             if (__any(mx - m > 6.0f)) {
;                 const float mnew = fmaxf(m, mx), alpha = __builtin_amdgcn_exp2f(m - mnew); m = mnew; l *= alpha;
; #pragma unroll
;                 for (int d = 0; d < 4; ++d)
; #pragma unroll
;                     for (int i = 0; i < 16; ++i) o[d][i] *= alpha;
;             }
.LBB0_428:
	v_max3_f32 v206, v80, s23, v81
	v_max3_f32 v206, v206, v82, v83
	v_max3_f32 v206, v206, v84, v85
	v_max3_f32 v206, v206, v86, v87
	v_max3_f32 v206, v206, v88, v89
	v_max3_f32 v206, v206, v90, v91
	v_max3_f32 v206, v206, v92, v93
	v_max3_f32 v206, v206, v94, v95
	s_nop 0
	v_max3_f32 v206, v206, v96, v97
	v_max3_f32 v206, v206, v98, v99
	v_max3_f32 v206, v206, v100, v101
	v_max3_f32 v206, v206, v102, v103
	v_max3_f32 v206, v206, v104, v105
	v_max3_f32 v206, v206, v106, v107
	v_max3_f32 v206, v206, v108, v109
	v_max3_f32 v206, v206, v110, v111
	v_mov_b32_e32 v207, v206
	s_nop 1
	v_permlane32_swap_b32_e32 v206, v207
	v_max_f32_e32 v207, v207, v207
	v_max_f32_e32 v206, v206, v207
	v_sub_f32_e32 v207, v206, v205
	v_cmp_lt_f32_e32 vcc, s24, v207
	s_cbranch_vccz .LBB0_423
	v_max_f32_e32 v206, v206, v206
	v_max_f32_e32 v207, v205, v205
	v_max_f32_e32 v207, v207, v206
	v_sub_f32_e32 v205, v205, v207
	v_exp_f32_e32 v206, v205
	v_mov_b32_e32 v205, v207
	v_pk_mul_f32 v[78:79], v[78:79], v[206:207] op_sel_hi:[1,0]
	v_pk_mul_f32 v[76:77], v[76:77], v[206:207] op_sel_hi:[1,0]
	v_pk_mul_f32 v[74:75], v[74:75], v[206:207] op_sel_hi:[1,0]
	v_pk_mul_f32 v[72:73], v[72:73], v[206:207] op_sel_hi:[1,0]
	v_pk_mul_f32 v[70:71], v[70:71], v[206:207] op_sel_hi:[1,0]
	v_pk_mul_f32 v[68:69], v[68:69], v[206:207] op_sel_hi:[1,0]
	v_pk_mul_f32 v[66:67], v[66:67], v[206:207] op_sel_hi:[1,0]
	v_pk_mul_f32 v[64:65], v[64:65], v[206:207] op_sel_hi:[1,0]
	v_pk_mul_f32 v[62:63], v[62:63], v[206:207] op_sel_hi:[1,0]
	v_pk_mul_f32 v[60:61], v[60:61], v[206:207] op_sel_hi:[1,0]
	v_pk_mul_f32 v[58:59], v[58:59], v[206:207] op_sel_hi:[1,0]
	v_pk_mul_f32 v[56:57], v[56:57], v[206:207] op_sel_hi:[1,0]
	v_pk_mul_f32 v[54:55], v[54:55], v[206:207] op_sel_hi:[1,0]
	v_pk_mul_f32 v[52:53], v[52:53], v[206:207] op_sel_hi:[1,0]
	v_pk_mul_f32 v[50:51], v[50:51], v[206:207] op_sel_hi:[1,0]
	v_pk_mul_f32 v[48:49], v[48:49], v[206:207] op_sel_hi:[1,0]
	v_pk_mul_f32 v[46:47], v[46:47], v[206:207] op_sel_hi:[1,0]
	v_pk_mul_f32 v[44:45], v[44:45], v[206:207] op_sel_hi:[1,0]
	v_pk_mul_f32 v[42:43], v[42:43], v[206:207] op_sel_hi:[1,0]
	v_pk_mul_f32 v[40:41], v[40:41], v[206:207] op_sel_hi:[1,0]
	v_pk_mul_f32 v[38:39], v[38:39], v[206:207] op_sel_hi:[1,0]
	v_pk_mul_f32 v[36:37], v[36:37], v[206:207] op_sel_hi:[1,0]
	v_pk_mul_f32 v[34:35], v[34:35], v[206:207] op_sel_hi:[1,0]
	v_pk_mul_f32 v[32:33], v[32:33], v[206:207] op_sel_hi:[1,0]
	v_pk_mul_f32 v[30:31], v[30:31], v[206:207] op_sel_hi:[1,0]
	v_pk_mul_f32 v[28:29], v[28:29], v[206:207] op_sel_hi:[1,0]
	v_pk_mul_f32 v[26:27], v[26:27], v[206:207] op_sel_hi:[1,0]
	v_pk_mul_f32 v[24:25], v[24:25], v[206:207] op_sel_hi:[1,0]
	v_pk_mul_f32 v[22:23], v[22:23], v[206:207] op_sel_hi:[1,0]
	v_pk_mul_f32 v[20:21], v[20:21], v[206:207] op_sel_hi:[1,0]
	v_pk_mul_f32 v[18:19], v[18:19], v[206:207] op_sel_hi:[1,0]
	v_pk_mul_f32 v[16:17], v[16:17], v[206:207] op_sel_hi:[1,0]
	v_mul_f32_e32 v204, v204, v206
	s_branch .LBB0_423

; DI void attn_block(const bf16_t* Q, const bf16_t* Kb, const bf16_t* Vt, bf16_t* AO, LAS unsigned char* lds, int bh, int qb, int tid, int wave, int lane) {
;     ...
;             float mx = -1e30f;
; #pragma unroll
;             for (int kb = 0; kb < 2; ++kb)
; #pragma unroll
;                 for (int i = 0; i < 16; ++i) mx = fmaxf(mx, sa[kb][i]);
;             mx = fmaxf(mx, __shfl_xor(mx, 32));
;             if (__any(mx - m > 6.0f)) {
;                 const float mnew = fmaxf(m, mx), alpha = __builtin_amdgcn_exp2f(m - mnew); m = mnew; l *= alpha;
; #pragma unroll
;                 for (int d = 0; d < 4; ++d)
; #pragma unroll
;                     for (int i = 0; i < 16; ++i) o[d][i] *= alpha;
;             }
.LBB0_433:
	v_max3_f32 v1, v80, s23, v81
	v_max3_f32 v1, v1, v82, v83
	v_max3_f32 v1, v1, v84, v85
	v_max3_f32 v1, v1, v86, v87
	v_max3_f32 v1, v1, v88, v89
	v_max3_f32 v1, v1, v90, v91
	v_max3_f32 v1, v1, v92, v93
	v_max3_f32 v1, v1, v94, v95
	s_nop 0
	v_max3_f32 v1, v1, v96, v97
	v_max3_f32 v1, v1, v98, v99
	v_max3_f32 v1, v1, v100, v101
	v_max3_f32 v1, v1, v102, v103
	v_max3_f32 v1, v1, v104, v105
	v_max3_f32 v1, v1, v106, v107
	v_max3_f32 v1, v1, v108, v109
	v_max3_f32 v1, v1, v110, v111
	v_mov_b32_e32 v2, v1
	s_nop 1
	v_permlane32_swap_b32_e32 v1, v2
	v_max_f32_e32 v2, v2, v2
	v_max_f32_e32 v1, v1, v2
	v_sub_f32_e32 v2, v1, v205
	v_cmp_lt_f32_e32 vcc, s24, v2
	s_cbranch_vccz .LBB0_435
	v_max_f32_e32 v1, v1, v1
	v_max_f32_e32 v2, v205, v205
	v_max_f32_e32 v1, v2, v1
	v_sub_f32_e32 v2, v205, v1
	v_exp_f32_e32 v2, v2
	v_mov_b32_e32 v205, v1
	v_pk_mul_f32 v[78:79], v[78:79], v[2:3] op_sel_hi:[1,0]
	v_pk_mul_f32 v[76:77], v[76:77], v[2:3] op_sel_hi:[1,0]
	v_pk_mul_f32 v[74:75], v[74:75], v[2:3] op_sel_hi:[1,0]
	v_pk_mul_f32 v[72:73], v[72:73], v[2:3] op_sel_hi:[1,0]
	v_pk_mul_f32 v[70:71], v[70:71], v[2:3] op_sel_hi:[1,0]
	v_pk_mul_f32 v[68:69], v[68:69], v[2:3] op_sel_hi:[1,0]
	v_pk_mul_f32 v[66:67], v[66:67], v[2:3] op_sel_hi:[1,0]
	v_pk_mul_f32 v[64:65], v[64:65], v[2:3] op_sel_hi:[1,0]
	v_pk_mul_f32 v[62:63], v[62:63], v[2:3] op_sel_hi:[1,0]
	v_pk_mul_f32 v[60:61], v[60:61], v[2:3] op_sel_hi:[1,0]
	v_pk_mul_f32 v[58:59], v[58:59], v[2:3] op_sel_hi:[1,0]
	v_pk_mul_f32 v[56:57], v[56:57], v[2:3] op_sel_hi:[1,0]
	v_pk_mul_f32 v[54:55], v[54:55], v[2:3] op_sel_hi:[1,0]
	v_pk_mul_f32 v[52:53], v[52:53], v[2:3] op_sel_hi:[1,0]
	v_pk_mul_f32 v[50:51], v[50:51], v[2:3] op_sel_hi:[1,0]
	v_pk_mul_f32 v[48:49], v[48:49], v[2:3] op_sel_hi:[1,0]
	v_pk_mul_f32 v[46:47], v[46:47], v[2:3] op_sel_hi:[1,0]
	v_pk_mul_f32 v[44:45], v[44:45], v[2:3] op_sel_hi:[1,0]
	v_pk_mul_f32 v[42:43], v[42:43], v[2:3] op_sel_hi:[1,0]
	v_pk_mul_f32 v[40:41], v[40:41], v[2:3] op_sel_hi:[1,0]
	v_pk_mul_f32 v[38:39], v[38:39], v[2:3] op_sel_hi:[1,0]
	v_pk_mul_f32 v[36:37], v[36:37], v[2:3] op_sel_hi:[1,0]
	v_pk_mul_f32 v[34:35], v[34:35], v[2:3] op_sel_hi:[1,0]
	v_pk_mul_f32 v[32:33], v[32:33], v[2:3] op_sel_hi:[1,0]
	v_pk_mul_f32 v[30:31], v[30:31], v[2:3] op_sel_hi:[1,0]
	v_pk_mul_f32 v[28:29], v[28:29], v[2:3] op_sel_hi:[1,0]
	v_pk_mul_f32 v[26:27], v[26:27], v[2:3] op_sel_hi:[1,0]
	v_pk_mul_f32 v[24:25], v[24:25], v[2:3] op_sel_hi:[1,0]
	v_pk_mul_f32 v[22:23], v[22:23], v[2:3] op_sel_hi:[1,0]
	v_pk_mul_f32 v[20:21], v[20:21], v[2:3] op_sel_hi:[1,0]
	v_pk_mul_f32 v[18:19], v[18:19], v[2:3] op_sel_hi:[1,0]
	v_pk_mul_f32 v[16:17], v[16:17], v[2:3] op_sel_hi:[1,0]
	v_mul_f32_e32 v204, v204, v2

; DI void attn_block(const bf16_t* Q, const bf16_t* Kb, const bf16_t* Vt, bf16_t* AO, LAS unsigned char* lds, int bh, int qb, int tid, int wave, int lane) {
;     ...
;             float mx = -1e30f;
; #pragma unroll
;             for (int kb = 0; kb < 2; ++kb)
; #pragma unroll
;                 for (int i = 0; i < 16; ++i) mx = fmaxf(mx, sa[kb][i]);
;             mx = fmaxf(mx, __shfl_xor(mx, 32));
;             if (__any(mx - m > 6.0f)) {
;                 const float mnew = fmaxf(m, mx), alpha = __builtin_amdgcn_exp2f(m - mnew); m = mnew; l *= alpha;
; #pragma unroll
;                 for (int d = 0; d < 4; ++d)
; #pragma unroll
;                     for (int i = 0; i < 16; ++i) o[d][i] *= alpha;
;             }
.LBB0_442:
	v_max3_f32 v1, v80, s23, v81
	v_max3_f32 v1, v1, v82, v83
	v_max3_f32 v1, v1, v84, v85
	v_max3_f32 v1, v1, v86, v87
	v_max3_f32 v1, v1, v88, v89
	v_max3_f32 v1, v1, v90, v91
	v_max3_f32 v1, v1, v92, v93
	v_max3_f32 v1, v1, v94, v95
	s_nop 0
	v_max3_f32 v1, v1, v96, v97
	v_max3_f32 v1, v1, v98, v99
	v_max3_f32 v1, v1, v100, v101
	v_max3_f32 v1, v1, v102, v103
	v_max3_f32 v1, v1, v104, v105
	v_max3_f32 v1, v1, v106, v107
	v_max3_f32 v1, v1, v108, v109
	v_max3_f32 v1, v1, v110, v111
	v_mov_b32_e32 v14, v1
	s_nop 1
	v_permlane32_swap_b32_e32 v1, v14
	v_max_f32_e32 v14, v14, v14
	v_max_f32_e32 v1, v1, v14
	v_sub_f32_e32 v14, v1, v189
	v_cmp_lt_f32_e32 vcc, s24, v14
	s_cbranch_vccz .LBB0_437
	v_max_f32_e32 v1, v1, v1
	v_max_f32_e32 v14, v189, v189
	v_max_f32_e32 v1, v14, v1
	v_sub_f32_e32 v14, v189, v1
	v_exp_f32_e32 v14, v14
	v_mov_b32_e32 v189, v1
	v_pk_mul_f32 v[78:79], v[78:79], v[14:15] op_sel_hi:[1,0]
	v_pk_mul_f32 v[76:77], v[76:77], v[14:15] op_sel_hi:[1,0]
	v_pk_mul_f32 v[74:75], v[74:75], v[14:15] op_sel_hi:[1,0]
	v_pk_mul_f32 v[72:73], v[72:73], v[14:15] op_sel_hi:[1,0]
	v_pk_mul_f32 v[70:71], v[70:71], v[14:15] op_sel_hi:[1,0]
	v_pk_mul_f32 v[68:69], v[68:69], v[14:15] op_sel_hi:[1,0]
	v_pk_mul_f32 v[66:67], v[66:67], v[14:15] op_sel_hi:[1,0]
	v_pk_mul_f32 v[64:65], v[64:65], v[14:15] op_sel_hi:[1,0]
	v_pk_mul_f32 v[62:63], v[62:63], v[14:15] op_sel_hi:[1,0]
	v_pk_mul_f32 v[60:61], v[60:61], v[14:15] op_sel_hi:[1,0]
	v_pk_mul_f32 v[58:59], v[58:59], v[14:15] op_sel_hi:[1,0]
	v_pk_mul_f32 v[56:57], v[56:57], v[14:15] op_sel_hi:[1,0]
	v_pk_mul_f32 v[54:55], v[54:55], v[14:15] op_sel_hi:[1,0]
	v_pk_mul_f32 v[52:53], v[52:53], v[14:15] op_sel_hi:[1,0]
	v_pk_mul_f32 v[50:51], v[50:51], v[14:15] op_sel_hi:[1,0]
	v_pk_mul_f32 v[48:49], v[48:49], v[14:15] op_sel_hi:[1,0]
	v_pk_mul_f32 v[46:47], v[46:47], v[14:15] op_sel_hi:[1,0]
	v_pk_mul_f32 v[44:45], v[44:45], v[14:15] op_sel_hi:[1,0]
	v_pk_mul_f32 v[42:43], v[42:43], v[14:15] op_sel_hi:[1,0]
	v_pk_mul_f32 v[40:41], v[40:41], v[14:15] op_sel_hi:[1,0]
	v_pk_mul_f32 v[38:39], v[38:39], v[14:15] op_sel_hi:[1,0]
	v_pk_mul_f32 v[36:37], v[36:37], v[14:15] op_sel_hi:[1,0]
	v_pk_mul_f32 v[34:35], v[34:35], v[14:15] op_sel_hi:[1,0]
	v_pk_mul_f32 v[32:33], v[32:33], v[14:15] op_sel_hi:[1,0]
	v_pk_mul_f32 v[30:31], v[30:31], v[14:15] op_sel_hi:[1,0]
	v_pk_mul_f32 v[28:29], v[28:29], v[14:15] op_sel_hi:[1,0]
	v_pk_mul_f32 v[26:27], v[26:27], v[14:15] op_sel_hi:[1,0]
	v_pk_mul_f32 v[24:25], v[24:25], v[14:15] op_sel_hi:[1,0]
	v_pk_mul_f32 v[22:23], v[22:23], v[14:15] op_sel_hi:[1,0]
	v_pk_mul_f32 v[20:21], v[20:21], v[14:15] op_sel_hi:[1,0]
	v_pk_mul_f32 v[18:19], v[18:19], v[14:15] op_sel_hi:[1,0]
	v_pk_mul_f32 v[16:17], v[16:17], v[14:15] op_sel_hi:[1,0]
	v_mul_f32_e32 v188, v188, v14
	s_branch .LBB0_437

; DI void attn_block(const bf16_t* Q, const bf16_t* Kb, const bf16_t* Vt, bf16_t* AO, LAS unsigned char* lds, int bh, int qb, int tid, int wave, int lane) {
;     ...
;             float mx = -1e30f;
; #pragma unroll
;             for (int kb = 0; kb < 2; ++kb)
; #pragma unroll
;                 for (int i = 0; i < 16; ++i) mx = fmaxf(mx, sa[kb][i]);
;             mx = fmaxf(mx, __shfl_xor(mx, 32));
;             if (__any(mx - m > 6.0f)) {
;                 const float mnew = fmaxf(m, mx), alpha = __builtin_amdgcn_exp2f(m - mnew); m = mnew; l *= alpha;
; #pragma unroll
;                 for (int d = 0; d < 4; ++d)
; #pragma unroll
;                     for (int i = 0; i < 16; ++i) o[d][i] *= alpha;
;             }
.LBB0_447:
	v_max3_f32 v1, v80, s23, v81
	v_max3_f32 v1, v1, v82, v83
	v_max3_f32 v1, v1, v84, v85
	v_max3_f32 v1, v1, v86, v87
	v_max3_f32 v1, v1, v88, v89
	v_max3_f32 v1, v1, v90, v91
	v_max3_f32 v1, v1, v92, v93
	v_max3_f32 v1, v1, v94, v95
	s_nop 0
	v_max3_f32 v1, v1, v96, v97
	v_max3_f32 v1, v1, v98, v99
	v_max3_f32 v1, v1, v100, v101
	v_max3_f32 v1, v1, v102, v103
	v_max3_f32 v1, v1, v104, v105
	v_max3_f32 v1, v1, v106, v107
	v_max3_f32 v1, v1, v108, v109
	v_max3_f32 v1, v1, v110, v111
	v_mov_b32_e32 v2, v1
	s_nop 1
	v_permlane32_swap_b32_e32 v1, v2
	v_max_f32_e32 v2, v2, v2
	v_max_f32_e32 v1, v1, v2
	v_sub_f32_e32 v2, v1, v189
	v_cmp_lt_f32_e32 vcc, s24, v2
	s_cbranch_vccz .LBB0_420
	v_max_f32_e32 v1, v1, v1
	v_max_f32_e32 v2, v189, v189
	v_max_f32_e32 v1, v2, v1
	v_sub_f32_e32 v2, v189, v1
	v_exp_f32_e32 v2, v2
	v_mov_b32_e32 v189, v1
	v_pk_mul_f32 v[78:79], v[78:79], v[2:3] op_sel_hi:[1,0]
	v_pk_mul_f32 v[76:77], v[76:77], v[2:3] op_sel_hi:[1,0]
	v_pk_mul_f32 v[74:75], v[74:75], v[2:3] op_sel_hi:[1,0]
	v_pk_mul_f32 v[72:73], v[72:73], v[2:3] op_sel_hi:[1,0]
	v_pk_mul_f32 v[70:71], v[70:71], v[2:3] op_sel_hi:[1,0]
	v_pk_mul_f32 v[68:69], v[68:69], v[2:3] op_sel_hi:[1,0]
	v_pk_mul_f32 v[66:67], v[66:67], v[2:3] op_sel_hi:[1,0]
	v_pk_mul_f32 v[64:65], v[64:65], v[2:3] op_sel_hi:[1,0]
	v_pk_mul_f32 v[62:63], v[62:63], v[2:3] op_sel_hi:[1,0]
	v_pk_mul_f32 v[60:61], v[60:61], v[2:3] op_sel_hi:[1,0]
	v_pk_mul_f32 v[58:59], v[58:59], v[2:3] op_sel_hi:[1,0]
	v_pk_mul_f32 v[56:57], v[56:57], v[2:3] op_sel_hi:[1,0]
	v_pk_mul_f32 v[54:55], v[54:55], v[2:3] op_sel_hi:[1,0]
	v_pk_mul_f32 v[52:53], v[52:53], v[2:3] op_sel_hi:[1,0]
	v_pk_mul_f32 v[50:51], v[50:51], v[2:3] op_sel_hi:[1,0]
	v_pk_mul_f32 v[48:49], v[48:49], v[2:3] op_sel_hi:[1,0]
	v_pk_mul_f32 v[46:47], v[46:47], v[2:3] op_sel_hi:[1,0]
	v_pk_mul_f32 v[44:45], v[44:45], v[2:3] op_sel_hi:[1,0]
	v_pk_mul_f32 v[42:43], v[42:43], v[2:3] op_sel_hi:[1,0]
	v_pk_mul_f32 v[40:41], v[40:41], v[2:3] op_sel_hi:[1,0]
	v_pk_mul_f32 v[38:39], v[38:39], v[2:3] op_sel_hi:[1,0]
	v_pk_mul_f32 v[36:37], v[36:37], v[2:3] op_sel_hi:[1,0]
	v_pk_mul_f32 v[34:35], v[34:35], v[2:3] op_sel_hi:[1,0]
	v_pk_mul_f32 v[32:33], v[32:33], v[2:3] op_sel_hi:[1,0]
	v_pk_mul_f32 v[30:31], v[30:31], v[2:3] op_sel_hi:[1,0]
	v_pk_mul_f32 v[28:29], v[28:29], v[2:3] op_sel_hi:[1,0]
	v_pk_mul_f32 v[26:27], v[26:27], v[2:3] op_sel_hi:[1,0]
	v_pk_mul_f32 v[24:25], v[24:25], v[2:3] op_sel_hi:[1,0]
	v_pk_mul_f32 v[22:23], v[22:23], v[2:3] op_sel_hi:[1,0]
	v_pk_mul_f32 v[20:21], v[20:21], v[2:3] op_sel_hi:[1,0]
	v_pk_mul_f32 v[18:19], v[18:19], v[2:3] op_sel_hi:[1,0]
	v_pk_mul_f32 v[16:17], v[16:17], v[2:3] op_sel_hi:[1,0]
	v_mul_f32_e32 v188, v188, v2
	s_branch .LBB0_420
